# GEMM tile order: 4x4 tile block per XCD per round for all GEMM phases including N=2048 ones (bit rotation of the XCD-major tile id)
# speedup vs baseline: 1.0202x; 1.0009x over previous
.LBB0_177:
	v_writelane_b32 v254, s30, 44
	v_mov_b32_e32 v12, v247
	s_nop 0
	v_writelane_b32 v254, s31, 45
	v_writelane_b32 v254, s20, 46
	v_writelane_b32 v254, s13, 47
	v_writelane_b32 v254, s54, 48
	v_writelane_b32 v254, s88, 49
	s_load_dwordx4 s[8:11], s[88:89], 0x78
	s_nop 0
	v_writelane_b32 v254, s89, 50
	s_lshl_b32 s88, s49, 3
	s_waitcnt lgkmcnt(0)
	v_writelane_b32 v254, s8, 51
	s_add_i32 s12, s88, 0xffff
	s_nop 0
	v_writelane_b32 v254, s9, 52
	v_writelane_b32 v254, s10, 53
	v_writelane_b32 v254, s11, 54
	v_readlane_b32 s9, v253, 9
	s_mul_i32 s9, s9, s49
	v_readlane_b32 s10, v253, 7
	s_or_b32 s9, s9, s10
	s_bfe_u32 s11, s9, 0x30002
	s_lshl_b32 s13, s11, 1
	s_and_b32 s13, s13, 6
	s_lshr_b32 s11, s11, 2
	s_or_b32 s11, s11, s13
	s_lshl_b32 s11, s11, 2
	s_andn2_b32 s9, s9, 0x1c
	s_or_b32 s9, s9, s11
	s_ff1_i32_b32 s10, s88
	s_lshr_b32 s10, s9, s10
	s_lshl_b32 s10, s10, 3
	s_sub_i32 s11, 16, s10
	s_min_i32 s11, s11, 8
	s_sext_i32_i16 s13, s11
	v_cvt_f32_i32_e32 v0, s13
	s_and_b32 s12, s9, s12
	s_sext_i32_i16 s9, s12
	v_cvt_f32_i32_e32 v1, s9
	v_rcp_iflag_f32_e32 v2, v0
	s_xor_b32 s9, s9, s13
	s_ashr_i32 s9, s9, 30
	s_or_b32 s9, s9, 1
	v_mul_f32_e32 v2, v1, v2
	v_trunc_f32_e32 v2, v2
	v_fma_f32 v1, -v2, v0, v1
	v_cvt_i32_f32_e32 v2, v2
	v_cmp_ge_f32_e64 s[20:21], |v1|, |v0|
	s_and_b64 s[20:21], s[20:21], exec
	s_cselect_b32 s9, s9, 0
	v_readfirstlane_b32 s13, v2
	s_add_i32 s13, s13, s9
	v_readfirstlane_b32 s8, v12
	s_sext_i32_i16 s46, s13
	s_and_b64 vcc, exec, s[2:3]
	s_cbranch_vccnz .LBB0_179
	v_cvt_f32_i32_e32 v0, s82
	v_cvt_f32_i32_e32 v1, s46
	s_xor_b32 s6, s46, s82
	s_ashr_i32 s6, s6, 30
	v_rcp_iflag_f32_e32 v2, v0
	s_or_b32 s9, s6, 1
	v_mul_f32_e32 v2, v1, v2
	v_trunc_f32_e32 v2, v2
	v_fma_f32 v1, -v2, v0, v1
	v_cvt_i32_f32_e32 v2, v2
	v_cmp_ge_f32_e64 s[6:7], |v1|, |v0|
	s_and_b64 s[6:7], s[6:7], exec
	s_cselect_b32 s6, s9, 0
	v_readfirstlane_b32 s7, v2
	s_add_i32 s6, s7, s6
	s_bfe_i64 s[6:7], s[6:7], 0x100000
	s_mul_i32 s7, s28, s7
	s_mul_hi_u32 s9, s28, s6
	s_add_i32 s7, s9, s7
	s_mul_i32 s6, s28, s6
	s_lshl_b64 s[6:7], s[6:7], 1

.LBB0_182:
	s_add_i32 s70, s87, 1
	s_ashr_i32 s71, s70, 31
	s_lshl_b64 s[2:3], s[70:71], 7
	s_or_b64 s[2:3], s[2:3], s[72:73]
	v_cmp_ge_i64_e64 s[4:5], s[2:3], v[222:223]
	s_mov_b64 s[62:63], s[72:73]
	v_cmp_lt_i64_e64 s[8:9], s[2:3], v[222:223]
	s_and_b64 vcc, exec, s[4:5]
	s_cbranch_vccnz .LBB0_184
	s_ashr_i32 s3, s2, 31
	s_lshr_b32 s3, s3, 29
	s_add_i32 s3, s2, s3
	s_ashr_i32 s6, s3, 3
	s_and_b32 s3, s3, -8
	s_sub_i32 s2, s2, s3
	s_waitcnt vmcnt(0)
	v_mov_b32_e32 v128, s2
	v_alignbit_b32 v128, s49, v128, 31
	v_readlane_b32 s7, v255, 1
	v_readfirstlane_b32 s3, v128
	s_mul_i32 s2, s3, s2
	s_add_i32 s2, s2, s6
	s_bfe_u32 s10, s2, 0x30002
	s_lshl_b32 s11, s10, 1
	s_and_b32 s11, s11, 6
	s_lshr_b32 s10, s10, 2
	s_or_b32 s10, s10, s11
	s_lshl_b32 s10, s10, 2
	s_andn2_b32 s2, s2, 0x1c
	s_or_b32 s2, s2, s10
	s_abs_i32 s6, s2
	s_mul_hi_u32 s7, s6, s7
	s_mul_i32 s10, s7, s88
	s_sub_i32 s6, s6, s10
	s_ashr_i32 s3, s2, 31
	s_add_i32 s10, s7, 1
	s_sub_i32 s11, s6, s88
	s_cmp_ge_u32 s6, s88
	s_cselect_b32 s7, s10, s7
	s_cselect_b32 s6, s11, s6
	s_add_i32 s10, s7, 1
	s_cmp_ge_u32 s6, s88
	s_cselect_b32 s6, s10, s7
	s_xor_b32 s6, s6, s3
	s_sub_i32 s3, s6, s3
	s_lshl_b32 s6, s3, 3
	s_sub_i32 s7, 16, s6
	s_min_i32 s7, s7, 8
	s_abs_i32 s10, s7
	v_cvt_f32_u32_e32 v128, s10
	s_sub_i32 s12, 0, s10
	s_mul_i32 s3, s3, s88
	s_sub_i32 s2, s2, s3
	v_rcp_iflag_f32_e32 v128, v128
	s_abs_i32 s11, s2
	s_xor_b32 s3, s2, s7
	s_ashr_i32 s3, s3, 31
	v_mul_f32_e32 v128, 0x4f7ffffe, v128
	v_cvt_u32_f32_e32 v128, v128
	s_nop 0
	v_readfirstlane_b32 s13, v128
	s_mul_i32 s12, s12, s13
	s_mul_hi_u32 s12, s13, s12
	s_add_i32 s13, s13, s12
	s_mul_hi_u32 s12, s11, s13
	s_mul_i32 s13, s12, s10
	s_sub_i32 s11, s11, s13
	s_add_i32 s13, s12, 1
	s_sub_i32 s24, s11, s10
	s_cmp_ge_u32 s11, s10
	s_cselect_b32 s12, s13, s12
	s_cselect_b32 s11, s24, s11
	s_add_i32 s13, s12, 1
	s_cmp_ge_u32 s11, s10
	s_cselect_b32 s10, s13, s12
	s_xor_b32 s10, s10, s3
	s_sub_i32 s33, s10, s3
	s_mul_i32 s3, s33, s7
	s_sub_i32 s2, s2, s3
	s_add_i32 s3, s6, s60
	s_add_i32 s50, s3, s2
	s_lshl_b32 s2, s70, 3
	s_add_i32 s33, s33, s2
	s_add_i32 s3, s49, -1
	s_and_b32 s33, s33, s3
